# v63 + dense-GQA attention steps: the older wave of each SIMD pair issues both K-tile LDS-DMA pieces (its own and its partner's via offset:64, M0 +0xfc0); the younger wave issues only its V piece
# speedup vs baseline: 1.0014x; 1.0014x over previous
.LBB0_399:
	s_setprio 3
	s_mov_b32 s30, s27
	s_mov_b32 s27, s72
	s_add_i32 s53, s30, 0
	v_add_u32_e32 v0, s53, v126
	ds_read_b128 v[34:37], v0
	ds_read_b128 v[38:41], v0 offset:2048
	s_add_i32 s34, s56, 0xfffc0000
	s_add_i32 s100, s55, -1
	s_and_b32 s34, s34, 0xf00000
	s_and_b32 s100, s100, 3
	s_lshl_b32 s78, s34, 1
	s_add_i32 s54, s29, 0
	s_mul_i32 s58, s100, 0x38000
	s_mov_b32 s59, s79
	s_add_u32 s98, s78, s58
	s_addc_u32 s99, s79, s79
	s_add_i32 s34, s54, s5
	v_lshl_add_u64 v[238:239], v[116:117], 0, s[98:99]
	s_mov_b32 m0, s34
	s_add_i32 s35, s34, 0x2000
	s_cmp_lt_u32 s5, 0x1000
	s_cbranch_scc0 .Lmy_skipk1
	global_load_lds_dwordx4 v[238:239], off
	s_add_i32 m0, s34, 0xfc0
	s_nop 0
	global_load_lds_dwordx4 v[238:239], off offset:64
.Lmy_skipk1:
	v_lshl_add_u64 v[238:239], v[118:119], 0, s[98:99]
	s_mov_b32 m0, s35
	s_nop 0
	global_load_lds_dwordx4 v[238:239], off
	v_exp_f32_e32 v145, v66
	v_exp_f32_e32 v146, v67
	v_exp_f32_e32 v147, v68
	v_exp_f32_e32 v148, v69
	v_exp_f32_e32 v149, v70
	v_exp_f32_e32 v150, v71
	v_exp_f32_e32 v151, v72
	s_waitcnt lgkmcnt(0)
	v_mfma_f32_32x32x16_bf16 v[82:97], v[34:37], v[110:113], v[50:65]
	ds_read_b128 v[34:37], v0 offset:4096
	v_exp_f32_e32 v152, v73
	v_exp_f32_e32 v153, v74
	v_exp_f32_e32 v154, v75
	v_exp_f32_e32 v155, v76
	v_exp_f32_e32 v156, v77
	v_exp_f32_e32 v157, v78
	v_mfma_f32_32x32x16_bf16 v[82:97], v[38:41], v[106:109], v[82:97]
	ds_read_b128 v[38:41], v0 offset:6144
	v_exp_f32_e32 v158, v79
	v_exp_f32_e32 v159, v80
	v_exp_f32_e32 v160, v81
	s_waitcnt lgkmcnt(0)
	v_mfma_f32_32x32x16_bf16 v[82:97], v[34:37], v[102:105], v[82:97]
	v_add_f32_e32 v34, v129, v131
	v_add_f32_e32 v66, v132, v34
	ds_read_b128 v[34:37], v0 offset:512
	ds_read_b128 v[42:45], v0 offset:2560
	ds_read_b128 v[46:49], v0 offset:4608
	v_mfma_f32_32x32x16_bf16 v[82:97], v[38:41], v[98:101], v[82:97]
	ds_read_b128 v[38:41], v0 offset:6656
	v_add_f32_e32 v0, v135, v66
	v_add_f32_e32 v0, v136, v0
	v_add_f32_e32 v0, v139, v0
	v_add_f32_e32 v0, v140, v0
	v_add_f32_e32 v0, v143, v0
	v_add_f32_e32 v0, v130, v0
	s_waitcnt lgkmcnt(0)
	v_mfma_f32_32x32x16_bf16 v[66:81], v[34:37], v[110:113], v[50:65]
	v_add_f32_e32 v0, v133, v0
	v_add_f32_e32 v0, v134, v0
	v_add_f32_e32 v0, v137, v0
	v_add_f32_e32 v0, v138, v0
	s_setprio 2
	v_add_f32_e32 v0, v141, v0
	v_add_f32_e32 v0, v142, v0
	v_add_f32_e32 v0, v144, v0
	v_mfma_f32_32x32x16_bf16 v[66:81], v[42:45], v[106:109], v[66:81]
	v_add_f32_e32 v0, v145, v0
	v_add_f32_e32 v0, v146, v0
	v_add_f32_e32 v0, v147, v0
	v_add_f32_e32 v0, v148, v0
	v_add_f32_e32 v0, v149, v0
	v_add_f32_e32 v0, v150, v0
	v_add_f32_e32 v0, v151, v0
	v_mfma_f32_32x32x16_bf16 v[66:81], v[46:49], v[102:105], v[66:81]
	v_add_f32_e32 v0, v152, v0
	v_add_f32_e32 v0, v153, v0
	v_add_f32_e32 v0, v154, v0
	v_add_f32_e32 v0, v155, v0
	v_add_f32_e32 v0, v156, v0
	v_add_f32_e32 v0, v157, v0
	v_add_f32_e32 v0, v158, v0
	v_mfma_f32_32x32x16_bf16 v[66:81], v[38:41], v[98:101], v[66:81]
	v_cvt_pk_bf16_f32 v34, v129, v131
	v_add_f32_e32 v161, v159, v0
	v_cvt_pk_bf16_f32 v35, v132, v135
	v_cvt_pk_bf16_f32 v36, v136, v139
	v_cvt_pk_bf16_f32 v37, v140, v143
	v_cvt_pk_bf16_f32 v38, v130, v133
	v_cvt_pk_bf16_f32 v39, v134, v137
	v_cvt_pk_bf16_f32 v40, v138, v141
	v_cvt_pk_bf16_f32 v41, v142, v144
	v_cvt_pk_bf16_f32 v42, v145, v146
	v_cvt_pk_bf16_f32 v43, v147, v148
	v_cvt_pk_bf16_f32 v44, v149, v150
	v_cvt_pk_bf16_f32 v45, v151, v152
	v_cvt_pk_bf16_f32 v46, v153, v154
	v_cvt_pk_bf16_f32 v47, v155, v156
	v_cvt_pk_bf16_f32 v48, v157, v158
	v_cvt_pk_bf16_f32 v49, v159, v160
	s_add_i32 s57, s72, 0
	v_add_u32_e32 v0, s57, v125
	ds_read_b64_tr_b16 v[130:131], v0 offset:8192
	ds_read_b64_tr_b16 v[132:133], v0 offset:8704
	ds_read_b64_tr_b16 v[134:135], v0 offset:12288
	v_max_f32_e32 v129, v67, v67
	s_waitcnt lgkmcnt(1)
	v_mfma_f32_32x32x16_bf16 v[18:33], v[130:133], v[34:37], v[18:33]
	ds_read_b64_tr_b16 v[136:137], v0 offset:12800
	ds_read_b64_tr_b16 v[130:131], v0 offset:9216
	s_waitcnt lgkmcnt(1)
	v_mfma_f32_32x32x16_bf16 v[2:17], v[134:137], v[34:37], v[2:17]
	ds_read_b64_tr_b16 v[132:133], v0 offset:9728
	ds_read_b64_tr_b16 v[34:35], v0 offset:13312
	s_waitcnt lgkmcnt(1)
	v_mfma_f32_32x32x16_bf16 v[18:33], v[130:133], v[38:41], v[18:33]
	ds_read_b64_tr_b16 v[36:37], v0 offset:13824
	ds_read_b64_tr_b16 v[130:131], v0 offset:10240
	s_waitcnt lgkmcnt(1)
	v_mfma_f32_32x32x16_bf16 v[2:17], v[34:37], v[38:41], v[2:17]
	ds_read_b64_tr_b16 v[132:133], v0 offset:10752
	ds_read_b64_tr_b16 v[34:35], v0 offset:11264
	ds_read_b64_tr_b16 v[36:37], v0 offset:11776
	ds_read_b64_tr_b16 v[38:39], v0 offset:14336
	ds_read_b64_tr_b16 v[40:41], v0 offset:14848
	ds_read_b64_tr_b16 v[134:135], v0 offset:15360
	ds_read_b64_tr_b16 v[136:137], v0 offset:15872
	s_waitcnt lgkmcnt(6)
	v_mfma_f32_32x32x16_bf16 v[18:33], v[130:133], v[42:45], v[18:33]
	v_max_f32_e32 v130, v83, v83
	v_max_f32_e32 v129, v130, v129
	v_max3_f32 v130, v82, v66, v84
	s_setprio 1
	v_max3_f32 v129, v129, v85, v69
	v_max3_f32 v130, v130, v68, v86
	v_max3_f32 v129, v129, v87, v71
	s_waitcnt lgkmcnt(2)
	v_mfma_f32_32x32x16_bf16 v[2:17], v[38:41], v[42:45], v[2:17]
	v_max3_f32 v38, v130, v70, v88
	v_max3_f32 v39, v129, v89, v73
	v_max3_f32 v38, v38, v72, v90
	v_max3_f32 v39, v39, v91, v75
	v_max3_f32 v38, v38, v74, v92
	v_max3_f32 v39, v39, v93, v77
	v_max3_f32 v38, v38, v76, v94
	v_mfma_f32_32x32x16_bf16 v[18:33], v[34:37], v[46:49], v[18:33]
	v_max3_f32 v34, v39, v95, v79
	v_max3_f32 v35, v38, v78, v96
	v_max3_f32 v34, v34, v97, v81
	v_add_f32_e32 v36, v160, v161
	v_max3_f32 v34, v35, v80, v34
	v_add_f32_e32 v128, v128, v36
	v_cmp_lt_f32_e32 vcc, s33, v34
	s_waitcnt lgkmcnt(0)
	v_mfma_f32_32x32x16_bf16 v[2:17], v[134:137], v[46:49], v[2:17]
	s_cbranch_vccz .LBB0_401
	v_mov_b32_e32 v35, v34
	s_nop 1
	v_permlane32_swap_b32 v34, v35
	s_nop 1
	s_nop 0
	v_max3_f32 v36, v34, v35, 0
	v_exp_f32_e64 v38, -v36
	v_add_f32_e32 v127, v127, v36
	v_xor_b32_e32 v34, 0x80000000, v127
	v_pk_add_f32 v[82:83], v[82:83], v[36:37] op_sel_hi:[1,0] neg_lo:[0,1] neg_hi:[0,1]
	v_pk_add_f32 v[66:67], v[66:67], v[36:37] op_sel_hi:[1,0] neg_lo:[0,1] neg_hi:[0,1]
	v_pk_add_f32 v[84:85], v[84:85], v[36:37] op_sel_hi:[1,0] neg_lo:[0,1] neg_hi:[0,1]
	v_pk_add_f32 v[68:69], v[68:69], v[36:37] op_sel_hi:[1,0] neg_lo:[0,1] neg_hi:[0,1]
	v_pk_add_f32 v[86:87], v[86:87], v[36:37] op_sel_hi:[1,0] neg_lo:[0,1] neg_hi:[0,1]
	v_pk_add_f32 v[70:71], v[70:71], v[36:37] op_sel_hi:[1,0] neg_lo:[0,1] neg_hi:[0,1]
	v_pk_add_f32 v[88:89], v[88:89], v[36:37] op_sel_hi:[1,0] neg_lo:[0,1] neg_hi:[0,1]
	v_pk_add_f32 v[72:73], v[72:73], v[36:37] op_sel_hi:[1,0] neg_lo:[0,1] neg_hi:[0,1]
	v_pk_add_f32 v[90:91], v[90:91], v[36:37] op_sel_hi:[1,0] neg_lo:[0,1] neg_hi:[0,1]
	v_pk_add_f32 v[74:75], v[74:75], v[36:37] op_sel_hi:[1,0] neg_lo:[0,1] neg_hi:[0,1]
	v_pk_add_f32 v[92:93], v[92:93], v[36:37] op_sel_hi:[1,0] neg_lo:[0,1] neg_hi:[0,1]
	v_pk_add_f32 v[76:77], v[76:77], v[36:37] op_sel_hi:[1,0] neg_lo:[0,1] neg_hi:[0,1]
	v_pk_add_f32 v[94:95], v[94:95], v[36:37] op_sel_hi:[1,0] neg_lo:[0,1] neg_hi:[0,1]
	v_pk_add_f32 v[78:79], v[78:79], v[36:37] op_sel_hi:[1,0] neg_lo:[0,1] neg_hi:[0,1]
	v_pk_add_f32 v[96:97], v[96:97], v[36:37] op_sel_hi:[1,0] neg_lo:[0,1] neg_hi:[0,1]
	v_pk_add_f32 v[80:81], v[80:81], v[36:37] op_sel_hi:[1,0] neg_lo:[0,1] neg_hi:[0,1]
	v_pk_mul_f32 v[32:33], v[32:33], v[38:39] op_sel_hi:[1,0]
	v_pk_mul_f32 v[30:31], v[30:31], v[38:39] op_sel_hi:[1,0]
	v_pk_mul_f32 v[28:29], v[28:29], v[38:39] op_sel_hi:[1,0]
	v_pk_mul_f32 v[26:27], v[26:27], v[38:39] op_sel_hi:[1,0]
	v_pk_mul_f32 v[24:25], v[24:25], v[38:39] op_sel_hi:[1,0]
	v_pk_mul_f32 v[22:23], v[22:23], v[38:39] op_sel_hi:[1,0]
	v_pk_mul_f32 v[20:21], v[20:21], v[38:39] op_sel_hi:[1,0]
	v_pk_mul_f32 v[18:19], v[18:19], v[38:39] op_sel_hi:[1,0]
	v_pk_mul_f32 v[16:17], v[16:17], v[38:39] op_sel_hi:[1,0]
	v_pk_mul_f32 v[14:15], v[14:15], v[38:39] op_sel_hi:[1,0]
	v_pk_mul_f32 v[12:13], v[12:13], v[38:39] op_sel_hi:[1,0]
	v_pk_mul_f32 v[10:11], v[10:11], v[38:39] op_sel_hi:[1,0]
	v_pk_mul_f32 v[8:9], v[8:9], v[38:39] op_sel_hi:[1,0]
	v_pk_mul_f32 v[6:7], v[6:7], v[38:39] op_sel_hi:[1,0]
	v_pk_mul_f32 v[4:5], v[4:5], v[38:39] op_sel_hi:[1,0]
	v_pk_mul_f32 v[2:3], v[2:3], v[38:39] op_sel_hi:[1,0]
	v_mul_f32_e32 v128, v128, v38
	v_mov_b32_e32 v35, v34
	v_mov_b32_e32 v36, v34
	v_mov_b32_e32 v37, v34
	v_mov_b32_e32 v38, v34
	v_mov_b32_e32 v39, v34
	v_mov_b32_e32 v40, v34
	v_mov_b32_e32 v41, v34
	v_mov_b32_e32 v42, v34
	v_mov_b32_e32 v43, v34
	v_mov_b32_e32 v44, v34
	v_mov_b32_e32 v45, v34
	v_mov_b32_e32 v46, v34
	v_mov_b32_e32 v47, v34
	v_mov_b32_e32 v48, v34
	v_mov_b32_e32 v49, v34
	v_mov_b32_e32 v50, v34
	v_mov_b32_e32 v51, v34
	v_mov_b32_e32 v52, v34
	v_mov_b32_e32 v53, v34
	v_mov_b32_e32 v54, v34
	v_mov_b32_e32 v55, v34
	v_mov_b32_e32 v56, v34
	v_mov_b32_e32 v57, v34
	v_mov_b32_e32 v58, v34
	v_mov_b32_e32 v59, v34
	v_mov_b32_e32 v60, v34
	v_mov_b32_e32 v61, v34
	v_mov_b32_e32 v62, v34
	v_mov_b32_e32 v63, v34
	v_mov_b32_e32 v64, v34
	v_mov_b32_e32 v65, v34
	s_branch .LBB0_402
.LBB0_401:
.LBB0_402:
	v_exp_f32_e32 v129, v82
	s_setprio 0
	v_exp_f32_e32 v146, v83
	v_exp_f32_e32 v147, v84
	v_exp_f32_e32 v148, v85
	v_exp_f32_e32 v149, v86
	v_exp_f32_e32 v150, v87
	v_exp_f32_e32 v151, v88
	v_exp_f32_e32 v152, v89
	v_exp_f32_e32 v153, v90
	v_exp_f32_e32 v154, v91
	v_exp_f32_e32 v155, v92
	v_exp_f32_e32 v156, v93
	v_exp_f32_e32 v157, v94
	v_exp_f32_e32 v158, v95
	v_exp_f32_e32 v159, v96
	v_exp_f32_e32 v160, v97
	s_add_i32 s58, s55, 4
	s_and_b32 s59, s56, 0xf00000
	s_and_b32 s58, s58, 3
	s_lshl_b32 s78, s59, 1
	s_mul_i32 s58, s58, 0x38000
	s_mov_b32 s59, s79
	s_add_u32 s98, s78, s58
	s_addc_u32 s99, s79, s79
	s_add_i32 s60, s57, s5
	v_lshl_add_u64 v[82:83], v[116:117], 0, s[98:99]
	s_mov_b32 m0, s60
	s_waitcnt vmcnt(0)
	s_barrier
	s_setprio 3
	v_add_u32_e32 v142, s54, v126
	ds_read_b128 v[130:133], v142
	ds_read_b128 v[134:137], v142 offset:2048
	s_cmp_lt_u32 s5, 0x1000
	s_cbranch_scc0 .Lmy_skipk2
	global_load_lds_dwordx4 v[82:83], off
	s_add_i32 m0, s60, 0xfc0
	s_nop 0
	global_load_lds_dwordx4 v[82:83], off offset:64
.Lmy_skipk2:
	v_lshl_add_u64 v[82:83], v[118:119], 0, s[98:99]
	s_add_i32 m0, s60, 0x2000
	s_nop 0
	global_load_lds_dwordx4 v[82:83], off
	v_exp_f32_e32 v161, v66
	v_exp_f32_e32 v162, v67
	v_exp_f32_e32 v163, v68
	v_exp_f32_e32 v164, v69
	ds_read_b128 v[66:69], v142 offset:4096
	v_exp_f32_e32 v165, v70
	v_exp_f32_e32 v166, v71
	s_waitcnt lgkmcnt(0)
	v_mfma_f32_32x32x16_bf16 v[82:97], v[130:133], v[110:113], v[50:65]
	v_exp_f32_e32 v167, v72
	v_exp_f32_e32 v168, v73
	ds_read_b128 v[70:73], v142 offset:6144
	v_exp_f32_e32 v169, v74
	v_exp_f32_e32 v170, v75
	v_exp_f32_e32 v171, v76
	v_exp_f32_e32 v172, v77
	v_mfma_f32_32x32x16_bf16 v[82:97], v[134:137], v[106:109], v[82:97]
	ds_read_b128 v[130:133], v142 offset:512
	ds_read_b128 v[134:137], v142 offset:2560
	ds_read_b128 v[138:141], v142 offset:4608
	ds_read_b128 v[142:145], v142 offset:6656
	v_exp_f32_e32 v173, v78
	v_exp_f32_e32 v174, v79
	v_exp_f32_e32 v175, v80
	v_exp_f32_e32 v176, v81
	v_mfma_f32_32x32x16_bf16 v[82:97], v[66:69], v[102:105], v[82:97]
	v_add_f32_e32 v66, v129, v146
	v_add_f32_e32 v66, v147, v66
	v_add_f32_e32 v66, v148, v66
	v_add_f32_e32 v66, v149, v66
	v_add_f32_e32 v66, v150, v66
	v_add_f32_e32 v66, v151, v66
	v_add_f32_e32 v66, v152, v66
	v_add_f32_e32 v66, v153, v66
	s_waitcnt lgkmcnt(0)
	v_mfma_f32_32x32x16_bf16 v[82:97], v[70:73], v[98:101], v[82:97]
	v_add_f32_e32 v177, v154, v66
	v_mfma_f32_32x32x16_bf16 v[66:81], v[130:133], v[110:113], v[50:65]
	v_add_f32_e32 v130, v155, v177
	v_add_f32_e32 v130, v156, v130
	v_add_f32_e32 v130, v157, v130
	v_add_f32_e32 v130, v158, v130
	v_add_f32_e32 v130, v159, v130
	v_add_f32_e32 v130, v160, v130
	v_add_f32_e32 v130, v161, v130
	v_mfma_f32_32x32x16_bf16 v[66:81], v[134:137], v[106:109], v[66:81]
	v_add_f32_e32 v130, v162, v130
	v_add_f32_e32 v130, v163, v130
	v_add_f32_e32 v130, v164, v130
	v_add_f32_e32 v130, v165, v130
	v_add_f32_e32 v130, v166, v130
	v_add_f32_e32 v130, v167, v130
	s_setprio 2
	v_add_f32_e32 v130, v168, v130
	v_mfma_f32_32x32x16_bf16 v[66:81], v[138:141], v[102:105], v[66:81]
	v_add_f32_e32 v130, v169, v130
	v_add_f32_e32 v130, v170, v130
	v_add_f32_e32 v130, v171, v130
	v_add_f32_e32 v130, v172, v130
	v_add_f32_e32 v130, v173, v130
	v_add_f32_e32 v130, v174, v130
	v_add_f32_e32 v177, v175, v130
	v_mfma_f32_32x32x16_bf16 v[66:81], v[142:145], v[98:101], v[66:81]
	v_cvt_pk_bf16_f32 v130, v129, v146
	v_cvt_pk_bf16_f32 v131, v147, v148
	v_cvt_pk_bf16_f32 v132, v149, v150
	v_cvt_pk_bf16_f32 v133, v151, v152
	v_cvt_pk_bf16_f32 v134, v153, v154
	v_cvt_pk_bf16_f32 v135, v155, v156
	v_cvt_pk_bf16_f32 v136, v157, v158
	v_cvt_pk_bf16_f32 v137, v159, v160
	v_cvt_pk_bf16_f32 v138, v161, v162
	v_cvt_pk_bf16_f32 v139, v163, v164
	v_cvt_pk_bf16_f32 v140, v165, v166
	v_cvt_pk_bf16_f32 v141, v167, v168
	v_cvt_pk_bf16_f32 v142, v169, v170
	v_cvt_pk_bf16_f32 v143, v171, v172
	v_cvt_pk_bf16_f32 v144, v173, v174
	v_cvt_pk_bf16_f32 v145, v175, v176
	v_add_u32_e32 v129, s53, v125
	ds_read_b64_tr_b16 v[146:147], v129 offset:8192
	ds_read_b64_tr_b16 v[148:149], v129 offset:8704
	ds_read_b64_tr_b16 v[150:151], v129 offset:12288
	s_waitcnt lgkmcnt(1)
	v_mfma_f32_32x32x16_bf16 v[18:33], v[146:149], v[130:133], v[18:33]
	ds_read_b64_tr_b16 v[152:153], v129 offset:12800
	ds_read_b64_tr_b16 v[146:147], v129 offset:9216
	s_waitcnt lgkmcnt(1)
	v_mfma_f32_32x32x16_bf16 v[2:17], v[150:153], v[130:133], v[2:17]
	ds_read_b64_tr_b16 v[148:149], v129 offset:9728
	ds_read_b64_tr_b16 v[130:131], v129 offset:13312
	s_waitcnt lgkmcnt(1)
	v_mfma_f32_32x32x16_bf16 v[18:33], v[146:149], v[134:137], v[18:33]
	ds_read_b64_tr_b16 v[132:133], v129 offset:13824
	ds_read_b64_tr_b16 v[146:147], v129 offset:10240
	s_waitcnt lgkmcnt(1)
	v_mfma_f32_32x32x16_bf16 v[2:17], v[130:133], v[134:137], v[2:17]
	ds_read_b64_tr_b16 v[148:149], v129 offset:10752
	ds_read_b64_tr_b16 v[130:131], v129 offset:11264
	ds_read_b64_tr_b16 v[132:133], v129 offset:11776
	ds_read_b64_tr_b16 v[134:135], v129 offset:14336
	ds_read_b64_tr_b16 v[136:137], v129 offset:14848
	ds_read_b64_tr_b16 v[150:151], v129 offset:15360
	ds_read_b64_tr_b16 v[152:153], v129 offset:15872
	v_max_f32_e32 v129, v67, v67
	s_waitcnt lgkmcnt(6)
	v_mfma_f32_32x32x16_bf16 v[18:33], v[146:149], v[138:141], v[18:33]
	v_max_f32_e32 v146, v83, v83
	v_max_f32_e32 v129, v146, v129
	v_max3_f32 v146, v82, v66, v84
	v_max3_f32 v129, v129, v85, v69
	v_max3_f32 v146, v146, v68, v86
	v_max3_f32 v129, v129, v87, v71
	v_max3_f32 v129, v129, v89, v73
	s_waitcnt lgkmcnt(2)
	s_setprio 1
	v_mfma_f32_32x32x16_bf16 v[2:17], v[134:137], v[138:141], v[2:17]
	v_max3_f32 v134, v146, v70, v88
	v_max3_f32 v134, v134, v72, v90
	v_max3_f32 v129, v129, v91, v75
	v_max3_f32 v134, v134, v74, v92
	v_max3_f32 v129, v129, v93, v77
	v_max3_f32 v134, v134, v76, v94
	v_max3_f32 v129, v129, v95, v79
	v_mfma_f32_32x32x16_bf16 v[18:33], v[130:133], v[142:145], v[18:33]
	v_max3_f32 v130, v134, v78, v96
	v_max3_f32 v129, v129, v97, v81
	v_add_f32_e32 v131, v176, v177
	v_max3_f32 v129, v130, v80, v129
	v_add_f32_e32 v128, v128, v131
	v_cmp_lt_f32_e32 vcc, s33, v129
	s_waitcnt lgkmcnt(0)
	v_mfma_f32_32x32x16_bf16 v[2:17], v[150:153], v[142:145], v[2:17]
	s_cbranch_vccz .LBB0_404
	v_mov_b32_e32 v34, v129
	s_nop 1
	v_permlane32_swap_b32 v129, v34
	s_nop 1
	s_nop 0
	v_max3_f32 v36, v129, v34, 0
	v_exp_f32_e64 v38, -v36
	v_add_f32_e32 v127, v127, v36
	v_xor_b32_e32 v34, 0x80000000, v127
	v_pk_add_f32 v[82:83], v[82:83], v[36:37] op_sel_hi:[1,0] neg_lo:[0,1] neg_hi:[0,1]
	v_pk_add_f32 v[84:85], v[84:85], v[36:37] op_sel_hi:[1,0] neg_lo:[0,1] neg_hi:[0,1]
	v_pk_add_f32 v[86:87], v[86:87], v[36:37] op_sel_hi:[1,0] neg_lo:[0,1] neg_hi:[0,1]
	v_pk_add_f32 v[88:89], v[88:89], v[36:37] op_sel_hi:[1,0] neg_lo:[0,1] neg_hi:[0,1]
	v_pk_add_f32 v[90:91], v[90:91], v[36:37] op_sel_hi:[1,0] neg_lo:[0,1] neg_hi:[0,1]
	v_pk_add_f32 v[92:93], v[92:93], v[36:37] op_sel_hi:[1,0] neg_lo:[0,1] neg_hi:[0,1]
	v_pk_add_f32 v[94:95], v[94:95], v[36:37] op_sel_hi:[1,0] neg_lo:[0,1] neg_hi:[0,1]
	v_pk_add_f32 v[96:97], v[96:97], v[36:37] op_sel_hi:[1,0] neg_lo:[0,1] neg_hi:[0,1]
	v_sub_f32_e32 v81, v81, v36
	v_sub_f32_e32 v80, v80, v36
	v_sub_f32_e32 v79, v79, v36
	v_sub_f32_e32 v78, v78, v36
	v_sub_f32_e32 v77, v77, v36
	v_sub_f32_e32 v76, v76, v36
	v_sub_f32_e32 v75, v75, v36
	v_sub_f32_e32 v74, v74, v36
	v_sub_f32_e32 v73, v73, v36
	v_sub_f32_e32 v72, v72, v36
	v_sub_f32_e32 v71, v71, v36
	v_sub_f32_e32 v70, v70, v36
	v_sub_f32_e32 v69, v69, v36
	v_sub_f32_e32 v68, v68, v36
	v_sub_f32_e32 v67, v67, v36
	v_sub_f32_e32 v66, v66, v36
	v_pk_mul_f32 v[32:33], v[32:33], v[38:39] op_sel_hi:[1,0]
	v_pk_mul_f32 v[30:31], v[30:31], v[38:39] op_sel_hi:[1,0]
	v_pk_mul_f32 v[28:29], v[28:29], v[38:39] op_sel_hi:[1,0]
	v_pk_mul_f32 v[26:27], v[26:27], v[38:39] op_sel_hi:[1,0]
	v_pk_mul_f32 v[24:25], v[24:25], v[38:39] op_sel_hi:[1,0]
	v_pk_mul_f32 v[22:23], v[22:23], v[38:39] op_sel_hi:[1,0]
	v_pk_mul_f32 v[20:21], v[20:21], v[38:39] op_sel_hi:[1,0]
	v_pk_mul_f32 v[18:19], v[18:19], v[38:39] op_sel_hi:[1,0]
	v_pk_mul_f32 v[16:17], v[16:17], v[38:39] op_sel_hi:[1,0]
	v_pk_mul_f32 v[14:15], v[14:15], v[38:39] op_sel_hi:[1,0]
	v_pk_mul_f32 v[12:13], v[12:13], v[38:39] op_sel_hi:[1,0]
	v_pk_mul_f32 v[10:11], v[10:11], v[38:39] op_sel_hi:[1,0]
	v_pk_mul_f32 v[8:9], v[8:9], v[38:39] op_sel_hi:[1,0]
	v_pk_mul_f32 v[6:7], v[6:7], v[38:39] op_sel_hi:[1,0]
	v_pk_mul_f32 v[4:5], v[4:5], v[38:39] op_sel_hi:[1,0]
	v_pk_mul_f32 v[2:3], v[2:3], v[38:39] op_sel_hi:[1,0]
	v_mul_f32_e32 v128, v128, v38
	v_mov_b32_e32 v35, v34
	v_mov_b32_e32 v36, v34
	v_mov_b32_e32 v37, v34
	v_mov_b32_e32 v38, v34
	v_mov_b32_e32 v39, v34
	v_mov_b32_e32 v40, v34
	v_mov_b32_e32 v41, v34
	v_mov_b32_e32 v42, v34
	v_mov_b32_e32 v43, v34
	v_mov_b32_e32 v44, v34
	v_mov_b32_e32 v45, v34
	v_mov_b32_e32 v46, v34
	v_mov_b32_e32 v47, v34
	v_mov_b32_e32 v48, v34
	v_mov_b32_e32 v49, v34
	v_mov_b32_e32 v50, v34
	v_mov_b32_e32 v51, v34
	v_mov_b32_e32 v52, v34
	v_mov_b32_e32 v53, v34
	v_mov_b32_e32 v54, v34
	v_mov_b32_e32 v55, v34
	v_mov_b32_e32 v56, v34
	v_mov_b32_e32 v57, v34
	v_mov_b32_e32 v58, v34
	v_mov_b32_e32 v59, v34
	v_mov_b32_e32 v60, v34
	v_mov_b32_e32 v61, v34
	v_mov_b32_e32 v62, v34
	v_mov_b32_e32 v63, v34
	v_mov_b32_e32 v64, v34
	v_mov_b32_e32 v65, v34
